# stack10 plus write-through sc0 sc1 on the Y stores (MODE 0 epilogue of out-proj and FFN2)
# speedup vs baseline: 1.0108x; 1.0108x over previous
; __device__ __forceinline__ unsigned pk2(float lo, float hi) { f32v2 v = {lo, hi}; bf16v2 r = __builtin_convertvector(v, bf16v2); return __builtin_bit_cast(unsigned, r); }
;     __device__ __forceinline__ void operator()(f32x4 (&acc)[2][2][4][2], const Unit& u, int wr, int wc, int fr, int fq) const {
;     ...
;         for (int ai = 0; ai < 2; ++ai)
; #pragma unroll
;             for (int m = 0; m < 4; ++m) {
;                 const size_t row = (size_t)(row0 + ai * HALF + m * 16);
; #pragma unroll
;                 for (int bj = 0; bj < 2; ++bj) {
;                     f32x4 v0 = acc[ai][bj][m][0], v1 = acc[ai][bj][m][1];
;                     const int cl = cl0 + bj * HALF;
;                     if constexpr (MODE == 0 || MODE == 1) {
;                         if (MODE == 1) {
; #pragma unroll
;                             for (int e = 0; e < 4; ++e) { const float a = fmaxf(v0[e], 0.f), b = fmaxf(v1[e], 0.f); v0[e] = a * a; v1[e] = b * b; }
;                         }
;                         u32x4 w; w.x = pk2(v0[0], v0[1]); w.y = pk2(v0[2], v0[3]); w.z = pk2(v1[0], v1[1]); w.w = pk2(v1[2], v1[3]);
;                         if constexpr (MODE == 1) __builtin_nontemporal_store(w, (u32x4*)(O + row * ldc + u.pn * BM + cl));
;                         else *(u32x4*)(O + row * ldc + u.pn * BM + cl) = w;
.LBB0_254:
	v_ashrrev_i32_e32 v147, 31, v146
	s_lshl_b32 s6, s70, 8
	v_cvt_pk_bf16_f32 v116, v116, v117
	v_cvt_pk_bf16_f32 v117, v118, v119
	v_cvt_pk_bf16_f32 v118, v112, v113
	v_or_b32_e32 v112, 16, v146
	v_cvt_pk_bf16_f32 v100, v100, v101
	v_cvt_pk_bf16_f32 v101, v102, v103
	v_cvt_pk_bf16_f32 v102, v96, v97
	v_or_b32_e32 v96, 32, v146
	v_cvt_pk_bf16_f32 v84, v84, v85
	v_cvt_pk_bf16_f32 v85, v86, v87
	v_cvt_pk_bf16_f32 v86, v80, v81
	v_or_b32_e32 v80, 48, v146
	v_lshlrev_b64 v[128:129], 11, v[146:147]
	s_ashr_i32 s7, s6, 31
	v_ashrrev_i32_e32 v113, 31, v112
	v_ashrrev_i32_e32 v97, 31, v96
	v_ashrrev_i32_e32 v81, 31, v80
	v_lshl_add_u64 v[128:129], s[90:91], 0, v[128:129]
	s_lshl_b64 s[6:7], s[6:7], 1
	v_lshlrev_b64 v[112:113], 11, v[112:113]
	v_lshlrev_b64 v[96:97], 11, v[96:97]
	v_lshlrev_b64 v[80:81], 11, v[80:81]
	v_cvt_pk_bf16_f32 v124, v124, v125
	v_cvt_pk_bf16_f32 v125, v126, v127
	v_cvt_pk_bf16_f32 v126, v120, v121
	v_lshl_add_u64 v[120:121], v[128:129], 0, s[6:7]
	v_lshlrev_b32_e32 v178, 1, v138
	v_lshl_add_u64 v[112:113], s[90:91], 0, v[112:113]
	v_lshl_add_u64 v[96:97], s[90:91], 0, v[96:97]
	v_lshl_add_u64 v[80:81], s[90:91], 0, v[80:81]
	v_lshl_add_u64 v[120:121], v[120:121], 0, v[178:179]
	v_cvt_pk_bf16_f32 v108, v108, v109
	v_cvt_pk_bf16_f32 v109, v110, v111
	v_cvt_pk_bf16_f32 v110, v104, v105
	v_lshl_add_u64 v[104:105], v[112:113], 0, s[6:7]
	v_cvt_pk_bf16_f32 v92, v92, v93
	v_cvt_pk_bf16_f32 v93, v94, v95
	v_cvt_pk_bf16_f32 v94, v88, v89
	v_lshl_add_u64 v[88:89], v[96:97], 0, s[6:7]
	v_cvt_pk_bf16_f32 v76, v76, v77
	v_cvt_pk_bf16_f32 v77, v78, v79
	v_cvt_pk_bf16_f32 v78, v72, v73
	v_lshl_add_u64 v[72:73], v[80:81], 0, s[6:7]
	s_mov_b64 s[6:7], 0x40000
	v_cvt_pk_bf16_f32 v60, v60, v61
	v_cvt_pk_bf16_f32 v61, v62, v63
	v_cvt_pk_bf16_f32 v62, v56, v57
	v_lshl_add_u64 v[56:57], v[120:121], 0, s[6:7]
	s_mov_b32 s6, 0x40000
	v_cvt_pk_bf16_f32 v63, v58, v59
	v_add_co_u32_e32 v58, vcc, s6, v120
	s_mov_b64 s[6:7], 0x48000
	s_nop 0
	v_addc_co_u32_e32 v59, vcc, 0, v121, vcc
	v_cvt_pk_bf16_f32 v44, v44, v45
	v_cvt_pk_bf16_f32 v45, v46, v47
	v_cvt_pk_bf16_f32 v46, v40, v41
	v_cvt_pk_bf16_f32 v47, v42, v43
	v_lshl_add_u64 v[40:41], v[120:121], 0, s[6:7]
	v_add_co_u32_e32 v42, vcc, s84, v120
	s_mov_b64 s[6:7], 0x50000
	s_nop 0
	v_addc_co_u32_e32 v43, vcc, 0, v121, vcc
	v_cvt_pk_bf16_f32 v28, v28, v29
	v_cvt_pk_bf16_f32 v29, v30, v31
	v_cvt_pk_bf16_f32 v30, v24, v25
	v_lshl_add_u64 v[24:25], v[120:121], 0, s[6:7]
	s_mov_b32 s6, 0x50000
	v_cvt_pk_bf16_f32 v31, v26, v27
	v_add_co_u32_e32 v26, vcc, s6, v120
	s_mov_b64 s[6:7], 0x58000
	s_nop 0
	v_addc_co_u32_e32 v27, vcc, 0, v121, vcc
	v_cvt_pk_bf16_f32 v12, v12, v13
	v_cvt_pk_bf16_f32 v13, v14, v15
	v_cvt_pk_bf16_f32 v14, v8, v9
	v_lshl_add_u64 v[8:9], v[120:121], 0, s[6:7]
	s_mov_b32 s6, 0x58000
	v_cvt_pk_bf16_f32 v15, v10, v11
	v_add_co_u32_e32 v10, vcc, s6, v120
	v_cvt_pk_bf16_f32 v127, v122, v123
	v_cvt_pk_bf16_f32 v119, v114, v115
	v_cvt_pk_bf16_f32 v111, v106, v107
	v_lshl_add_u64 v[104:105], v[104:105], 0, v[178:179]
	v_cvt_pk_bf16_f32 v103, v98, v99
	v_cvt_pk_bf16_f32 v95, v90, v91
	v_lshl_add_u64 v[88:89], v[88:89], 0, v[178:179]
	v_cvt_pk_bf16_f32 v87, v82, v83
	v_cvt_pk_bf16_f32 v79, v74, v75
	v_lshl_add_u64 v[72:73], v[72:73], 0, v[178:179]
	v_cvt_pk_bf16_f32 v68, v68, v69
	v_cvt_pk_bf16_f32 v69, v70, v71
	v_cvt_pk_bf16_f32 v70, v64, v65
	v_cvt_pk_bf16_f32 v71, v66, v67
	v_cvt_pk_bf16_f32 v52, v52, v53
	v_cvt_pk_bf16_f32 v53, v54, v55
	v_cvt_pk_bf16_f32 v54, v48, v49
	v_cvt_pk_bf16_f32 v55, v50, v51
	v_cvt_pk_bf16_f32 v36, v36, v37
	v_cvt_pk_bf16_f32 v37, v38, v39
	v_cvt_pk_bf16_f32 v38, v32, v33
	v_cvt_pk_bf16_f32 v39, v34, v35
	v_cvt_pk_bf16_f32 v20, v20, v21
	v_cvt_pk_bf16_f32 v21, v22, v23
	v_cvt_pk_bf16_f32 v22, v16, v17
	v_cvt_pk_bf16_f32 v23, v18, v19
	v_addc_co_u32_e32 v11, vcc, 0, v121, vcc
	v_cvt_pk_bf16_f32 v4, v4, v5
	v_cvt_pk_bf16_f32 v5, v6, v7
	v_cvt_pk_bf16_f32 v6, v0, v1
	v_cvt_pk_bf16_f32 v7, v2, v3
	global_store_dwordx4 v[120:121], v[124:127], off sc0 sc1
	global_store_dwordx4 v[120:121], v[116:119], off offset:256 sc0 sc1
	global_store_dwordx4 v[104:105], v[108:111], off sc0 sc1
	global_store_dwordx4 v[104:105], v[100:103], off offset:256 sc0 sc1
	global_store_dwordx4 v[88:89], v[92:95], off sc0 sc1
	global_store_dwordx4 v[88:89], v[84:87], off offset:256 sc0 sc1
	global_store_dwordx4 v[72:73], v[76:79], off sc0 sc1
	global_store_dwordx4 v[72:73], v[68:71], off offset:256 sc0 sc1
	global_store_dwordx4 v[58:59], v[60:63], off sc0 sc1
	global_store_dwordx4 v[56:57], v[52:55], off offset:256 sc0 sc1
	global_store_dwordx4 v[42:43], v[44:47], off sc0 sc1
	global_store_dwordx4 v[40:41], v[36:39], off offset:256 sc0 sc1
	global_store_dwordx4 v[26:27], v[28:31], off sc0 sc1
	global_store_dwordx4 v[24:25], v[20:23], off offset:256 sc0 sc1
	global_store_dwordx4 v[10:11], v[12:15], off sc0 sc1
	global_store_dwordx4 v[8:9], v[4:7], off offset:256 sc0 sc1
	s_andn2_b64 vcc, exec, s[4:5]
	s_mov_b64 s[4:5], -1
	s_cbranch_vccnz .LBB0_226
	s_branch .LBB0_565
